# v12 + K/V LDS staging writes moved mid-interval (after QK for waves 0-3, after deferred softmax+PV for waves 4-7)
# speedup vs baseline: 1.0053x; 1.0053x over previous
; template <int DQK, bool CAUSAL, bool ROPE> ...
;     ...
;     for (int j = 0; j < ntiles; ++j) {
;         const bool more = j + 1 < ntiles;
;         const int vnext = vcur == 2 ? 0 : vcur + 1;
;         if (more) AT_LOAD(j + 1);
.LBB0_883:
	s_mov_b32 s98, 0
	s_add_i32 s2, s1, 1
	s_cmp_lt_u32 s2, s33
	s_cselect_b64 s[66:67], -1, 0
	s_add_i32 s4, s1, 2
	s_cmp_ge_u32 s4, s33
	s_cbranch_scc1 .LBB0_885
	s_bitcmp1_b32 s1, 0
	s_cbranch_scc1 .Lld_setx
	global_load_dwordx4 v[166:169], v222, s[96:97]
	global_load_dwordx4 v[170:173], v220, s[96:97]
	global_load_dwordx4 v[180:183], v224, s[96:97]
	global_load_dwordx4 v[184:187], v228, s[96:97]
	global_load_dwordx4 v[188:191], v226, s[96:97]
	s_branch .LBB0_885

; template <int DQK, bool CAUSAL, bool ROPE> ...
;     ...
;         if (more) AT_STORE((j + 1) & 1, vnext);
.Ld2_exp:
	v_mul_f32_e32 v2, 0xbdd53b94, v252
	ds_read_b128 v[4:7], v17 offset:51200
	ds_read_b128 v[8:11], v17 offset:55808
	ds_read_b128 v[12:15], v17 offset:60416
	ds_read_b128 v[176:179], v17 offset:65024
	v_fmamk_f32 v98, v98, 0x3dd53b94, v2
	v_fmamk_f32 v99, v99, 0x3dd53b94, v2
	v_fmamk_f32 v100, v100, 0x3dd53b94, v2
	v_fmamk_f32 v101, v101, 0x3dd53b94, v2
	v_fmamk_f32 v102, v102, 0x3dd53b94, v2
	v_fmamk_f32 v103, v103, 0x3dd53b94, v2
	v_fmamk_f32 v104, v104, 0x3dd53b94, v2
	v_fmamk_f32 v105, v105, 0x3dd53b94, v2
	v_exp_f32_e32 v98, v98
	v_exp_f32_e32 v99, v99
	v_exp_f32_e32 v100, v100
	v_exp_f32_e32 v101, v101
	v_exp_f32_e32 v102, v102
	v_exp_f32_e32 v103, v103
	v_exp_f32_e32 v104, v104
	v_exp_f32_e32 v105, v105
	v_add_f32_e32 v16, v98, v99
	v_add_f32_e32 v16, v16, v100
	v_add_f32_e32 v16, v16, v101
	v_add_f32_e32 v16, v16, v102
	v_add_f32_e32 v16, v16, v103
	v_add_f32_e32 v16, v16, v104
	v_add_f32_e32 v16, v16, v105
	v_cvt_pk_bf16_f32 v98, v98, v99
	v_cvt_pk_bf16_f32 v99, v100, v101
	v_cvt_pk_bf16_f32 v100, v102, v103
	v_cvt_pk_bf16_f32 v101, v104, v105
	v_fmamk_f32 v106, v106, 0x3dd53b94, v2
	s_waitcnt lgkmcnt(3)
	v_mfma_f32_32x32x16_bf16 v[66:81], v[4:7], v[98:101], v[66:81]
	ds_read_b128 v[4:7], v17 offset:51232
	v_fmamk_f32 v107, v107, 0x3dd53b94, v2
	v_fmamk_f32 v108, v108, 0x3dd53b94, v2
	v_fmamk_f32 v109, v109, 0x3dd53b94, v2
	v_fmamk_f32 v110, v110, 0x3dd53b94, v2
	v_fmamk_f32 v111, v111, 0x3dd53b94, v2
	v_fmamk_f32 v112, v112, 0x3dd53b94, v2
	s_waitcnt lgkmcnt(3)
	v_mfma_f32_32x32x16_bf16 v[50:65], v[8:11], v[98:101], v[50:65]
	ds_read_b128 v[8:11], v17 offset:55840
	v_fmamk_f32 v113, v113, 0x3dd53b94, v2
	v_exp_f32_e32 v106, v106
	v_exp_f32_e32 v107, v107
	v_exp_f32_e32 v108, v108
	v_exp_f32_e32 v109, v109
	v_exp_f32_e32 v110, v110
	s_waitcnt lgkmcnt(3)
	v_mfma_f32_32x32x16_bf16 v[34:49], v[12:15], v[98:101], v[34:49]
	ds_read_b128 v[12:15], v17 offset:60448
	v_exp_f32_e32 v111, v111
	v_exp_f32_e32 v112, v112
	v_exp_f32_e32 v113, v113
	v_pk_add_f32 v[102:103], v[106:107], v[108:109]
	v_pk_add_f32 v[104:105], v[110:111], v[112:113]
	s_waitcnt lgkmcnt(3)
	v_mfma_f32_32x32x16_bf16 v[18:33], v[176:179], v[98:101], v[18:33]
	ds_read_b128 v[176:179], v17 offset:65056
	v_pk_add_f32 v[102:103], v[102:103], v[104:105]
	v_cvt_pk_bf16_f32 v106, v106, v107
	v_cvt_pk_bf16_f32 v107, v108, v109
	v_cvt_pk_bf16_f32 v108, v110, v111
	v_cvt_pk_bf16_f32 v109, v112, v113
	v_fmamk_f32 v82, v82, 0x3dd53b94, v2
	s_waitcnt lgkmcnt(3)
	v_mfma_f32_32x32x16_bf16 v[66:81], v[4:7], v[106:109], v[66:81]
	ds_read_b128 v[4:7], v17 offset:51264
	v_fmamk_f32 v83, v83, 0x3dd53b94, v2
	v_fmamk_f32 v84, v84, 0x3dd53b94, v2
	v_fmamk_f32 v85, v85, 0x3dd53b94, v2
	v_fmamk_f32 v86, v86, 0x3dd53b94, v2
	v_fmamk_f32 v87, v87, 0x3dd53b94, v2
	v_fmamk_f32 v88, v88, 0x3dd53b94, v2
	s_waitcnt lgkmcnt(3)
	v_mfma_f32_32x32x16_bf16 v[50:65], v[8:11], v[106:109], v[50:65]
	ds_read_b128 v[8:11], v17 offset:55872
	v_fmamk_f32 v89, v89, 0x3dd53b94, v2
	v_exp_f32_e32 v82, v82
	v_exp_f32_e32 v83, v83
	v_exp_f32_e32 v84, v84
	v_exp_f32_e32 v85, v85
	v_exp_f32_e32 v86, v86
	s_waitcnt lgkmcnt(3)
	v_mfma_f32_32x32x16_bf16 v[34:49], v[12:15], v[106:109], v[34:49]
	ds_read_b128 v[12:15], v17 offset:60480
	v_exp_f32_e32 v87, v87
	v_exp_f32_e32 v88, v88
	v_exp_f32_e32 v89, v89
	v_pk_add_f32 v[104:105], v[82:83], v[84:85]
	v_pk_add_f32 v[102:103], v[102:103], v[104:105]
	v_pk_add_f32 v[104:105], v[86:87], v[88:89]
	s_waitcnt lgkmcnt(3)
	v_mfma_f32_32x32x16_bf16 v[18:33], v[176:179], v[106:109], v[18:33]
	ds_read_b128 v[176:179], v17 offset:65088
	v_pk_add_f32 v[102:103], v[102:103], v[104:105]
	v_cvt_pk_bf16_f32 v82, v82, v83
	v_cvt_pk_bf16_f32 v83, v84, v85
	v_cvt_pk_bf16_f32 v84, v86, v87
	v_cvt_pk_bf16_f32 v85, v88, v89
	v_fmamk_f32 v90, v90, 0x3dd53b94, v2
	s_waitcnt lgkmcnt(3)
	v_mfma_f32_32x32x16_bf16 v[66:81], v[4:7], v[82:85], v[66:81]
	ds_read_b128 v[4:7], v17 offset:51296
	v_fmamk_f32 v91, v91, 0x3dd53b94, v2
	v_fmamk_f32 v92, v92, 0x3dd53b94, v2
	v_fmamk_f32 v93, v93, 0x3dd53b94, v2
	v_fmamk_f32 v94, v94, 0x3dd53b94, v2
	v_fmamk_f32 v95, v95, 0x3dd53b94, v2
	v_fmamk_f32 v96, v96, 0x3dd53b94, v2
	s_waitcnt lgkmcnt(3)
	v_mfma_f32_32x32x16_bf16 v[50:65], v[8:11], v[82:85], v[50:65]
	ds_read_b128 v[8:11], v17 offset:55904
	v_fmamk_f32 v97, v97, 0x3dd53b94, v2
	v_exp_f32_e32 v90, v90
	v_exp_f32_e32 v91, v91
	v_exp_f32_e32 v92, v92
	v_exp_f32_e32 v93, v93
	v_exp_f32_e32 v94, v94
	s_waitcnt lgkmcnt(3)
	v_mfma_f32_32x32x16_bf16 v[34:49], v[12:15], v[82:85], v[34:49]
	ds_read_b128 v[12:15], v17 offset:60512
	v_exp_f32_e32 v95, v95
	v_exp_f32_e32 v96, v96
	v_exp_f32_e32 v97, v97
	v_pk_add_f32 v[104:105], v[90:91], v[92:93]
	v_pk_add_f32 v[102:103], v[102:103], v[104:105]
	v_pk_add_f32 v[104:105], v[94:95], v[96:97]
	s_waitcnt lgkmcnt(3)
	v_mfma_f32_32x32x16_bf16 v[18:33], v[176:179], v[82:85], v[18:33]
	ds_read_b128 v[176:179], v17 offset:65120
	v_pk_add_f32 v[102:103], v[102:103], v[104:105]
	v_cvt_pk_bf16_f32 v90, v90, v91
	v_cvt_pk_bf16_f32 v91, v92, v93
	v_cvt_pk_bf16_f32 v92, v94, v95
	v_cvt_pk_bf16_f32 v93, v96, v97
	s_nop 0
	s_waitcnt lgkmcnt(3)
	v_mfma_f32_32x32x16_bf16 v[66:81], v[4:7], v[90:93], v[66:81]
	v_add_f32_e32 v16, v16, v102
	s_waitcnt lgkmcnt(2)
	v_mfma_f32_32x32x16_bf16 v[50:65], v[8:11], v[90:93], v[50:65]
	v_add_f32_e32 v16, v16, v103
	s_waitcnt lgkmcnt(1)
	v_mfma_f32_32x32x16_bf16 v[34:49], v[12:15], v[90:93], v[34:49]
	v_add_f32_e32 v250, v250, v16
	s_waitcnt lgkmcnt(0)
	v_mfma_f32_32x32x16_bf16 v[18:33], v[176:179], v[90:93], v[18:33]
	s_andn2_b64 vcc, exec, s[66:67]
	s_cbranch_vccnz .Lwb_done
	s_add_i32 s99, s71, 1
	s_cmp_lg_u32 s71, 2
	s_cselect_b32 s99, s99, 0
	s_bitcmp1_b32 s2, 0
	s_cselect_b32 s0, 0x6400, 0
	v_add_u32_e32 v2, s0, v235
	v_add_u32_e32 v4, v2, v238
	v_add_u32_e32 v5, v2, v239
	v_add3_u32 v6, s0, v240, v236
	s_mul_i32 s4, s99, 0x4800
	v_add_u32_e32 v2, s4, v241
	v_add_u32_e32 v7, v2, v242
	v_add_u32_e32 v2, v2, v243
	s_add_i32 s5, s2, 1
	s_cmp_lt_u32 s5, s33
	s_cbranch_scc1 .Lwb_wait5
	s_waitcnt vmcnt(0)
	s_branch .Lwb_go

; template <int DQK, bool CAUSAL, bool ROPE> ...
;     ...
;         if (grp == 1 && j > 0) AT_PV(j - 1, vprev);
;         AT_QKSM(j);
;         if (grp == 0) AT_PV(j, vcur);
;         if (more) AT_STORE((j + 1) & 1, vnext);
.Lwb_fin:
	s_mov_b32 s98, 1
.Lwb_done:
	s_branch .LBB0_893
.LBB0_887:
	s_or_b64 s[0:1], s[84:85], s[68:69]
	s_and_b64 vcc, exec, s[0:1]
	s_cbranch_vccnz .LBB0_889
.LBB0_889:
	s_add_i32 s0, s71, 1
	s_cmp_lg_u32 s71, 2
	s_cselect_b32 s1, s0, 0
	s_andn2_b64 vcc, exec, s[66:67]
	s_cbranch_vccnz .LBB0_891
	s_cmp_eq_u32 s98, 1
	s_cbranch_scc1 .LBB0_891
	s_bitcmp1_b32 s2, 0
	s_cselect_b32 s0, 0x6400, 0
	v_add_u32_e32 v2, s0, v235
	v_add_u32_e32 v4, v2, v238
	v_add_u32_e32 v5, v2, v239
	v_add3_u32 v6, s0, v240, v236
	s_mul_i32 s4, s1, 0x4800
	v_add_u32_e32 v2, s4, v241
	v_add_u32_e32 v7, v2, v242
	v_add_u32_e32 v2, v2, v243
	s_add_i32 s5, s2, 1
	s_cmp_lt_u32 s5, s33
	s_cbranch_scc1 .Lw_wait5
	s_waitcnt vmcnt(0)
	s_branch .Lw_go

; template <int DQK, bool CAUSAL, bool ROPE> ...
;     ...
;         if (more) AT_STORE((j + 1) & 1, vnext);
.LBB0_894:
	s_bitcmp1_b32 s1, 0
	s_cselect_b32 s0, 0x6400, 0
	v_add_u32_e32 v2, s0, v245
	ds_read_b128 v[4:7], v2
	ds_read_b128 v[8:11], v2 offset:32
	s_waitcnt lgkmcnt(1)
	v_mfma_f32_32x32x16_bf16 v[98:113], v[4:7], v[154:157], 0
	ds_read_b128 v[4:7], v2 offset:12800
	ds_read_b128 v[12:15], v2 offset:12832
	s_waitcnt lgkmcnt(1)
	v_mfma_f32_32x32x16_bf16 v[82:97], v[4:7], v[154:157], 0
	v_mfma_f32_32x32x16_bf16 v[98:113], v[8:11], v[126:129], v[98:113]
	ds_read_b128 v[4:7], v2 offset:64
	ds_read_b128 v[8:11], v2 offset:12864
	s_waitcnt lgkmcnt(2)
	v_mfma_f32_32x32x16_bf16 v[82:97], v[12:15], v[126:129], v[82:97]
	s_waitcnt lgkmcnt(1)
	v_mfma_f32_32x32x16_bf16 v[98:113], v[4:7], v[130:133], v[98:113]
	ds_read_b128 v[4:7], v2 offset:96
	ds_read_b128 v[12:15], v2 offset:12896
	s_waitcnt lgkmcnt(2)
	v_mfma_f32_32x32x16_bf16 v[82:97], v[8:11], v[130:133], v[82:97]
	s_waitcnt lgkmcnt(1)
	v_mfma_f32_32x32x16_bf16 v[98:113], v[4:7], v[134:137], v[98:113]
	ds_read_b128 v[4:7], v2 offset:128
	ds_read_b128 v[8:11], v2 offset:12928
	s_waitcnt lgkmcnt(2)
	v_mfma_f32_32x32x16_bf16 v[82:97], v[12:15], v[134:137], v[82:97]
	s_waitcnt lgkmcnt(1)
	v_mfma_f32_32x32x16_bf16 v[98:113], v[4:7], v[138:141], v[98:113]
	ds_read_b128 v[4:7], v2 offset:160
	ds_read_b128 v[12:15], v2 offset:12960
	s_waitcnt lgkmcnt(2)
	v_mfma_f32_32x32x16_bf16 v[82:97], v[8:11], v[138:141], v[82:97]
	s_waitcnt lgkmcnt(1)
	v_mfma_f32_32x32x16_bf16 v[98:113], v[4:7], v[142:145], v[98:113]
	ds_read_b128 v[4:7], v2 offset:192
	ds_read_b128 v[8:11], v2 offset:12992
	s_waitcnt lgkmcnt(2)
	v_mfma_f32_32x32x16_bf16 v[82:97], v[12:15], v[142:145], v[82:97]
	s_waitcnt lgkmcnt(1)
	v_mfma_f32_32x32x16_bf16 v[98:113], v[4:7], v[150:153], v[98:113]
	ds_read_b128 v[4:7], v2 offset:224
	ds_read_b128 v[12:15], v2 offset:13024
	s_waitcnt lgkmcnt(2)
	v_mfma_f32_32x32x16_bf16 v[82:97], v[8:11], v[150:153], v[82:97]
	s_waitcnt lgkmcnt(1)
	v_mfma_f32_32x32x16_bf16 v[98:113], v[4:7], v[118:121], v[98:113]
	ds_read_b128 v[4:7], v2 offset:256
	ds_read_b128 v[8:11], v2 offset:13056
	s_waitcnt lgkmcnt(2)
	v_mfma_f32_32x32x16_bf16 v[82:97], v[12:15], v[118:121], v[82:97]
	ds_read_b128 v[12:15], v249
	ds_read_b128 v[176:179], v2 offset:288
	s_waitcnt lgkmcnt(1)
	v_mfma_f32_32x32x16_bf16 v[98:113], v[4:7], v[12:15], v[98:113]
	ds_read_b128 v[4:7], v2 offset:13088
	v_mfma_f32_32x32x16_bf16 v[82:97], v[8:11], v[12:15], v[82:97]
	ds_read_b128 v[8:11], v249 offset:1024
	ds_read_b128 v[12:15], v2 offset:320
	s_waitcnt lgkmcnt(1)
	v_mfma_f32_32x32x16_bf16 v[98:113], v[176:179], v[8:11], v[98:113]
	ds_read_b128 v[176:179], v2 offset:13120
	v_mfma_f32_32x32x16_bf16 v[82:97], v[4:7], v[8:11], v[82:97]
	ds_read_b128 v[4:7], v249 offset:2048
	ds_read_b128 v[8:11], v2 offset:352
	s_waitcnt lgkmcnt(1)
	v_mfma_f32_32x32x16_bf16 v[98:113], v[12:15], v[4:7], v[98:113]
	ds_read_b128 v[12:15], v2 offset:13152
	v_mfma_f32_32x32x16_bf16 v[82:97], v[176:179], v[4:7], v[82:97]
	ds_read_b128 v[4:7], v249 offset:3072
	s_waitcnt lgkmcnt(0)
	v_mfma_f32_32x32x16_bf16 v[98:113], v[8:11], v[4:7], v[98:113]
	v_mfma_f32_32x32x16_bf16 v[82:97], v[12:15], v[4:7], v[82:97]
	s_and_b64 vcc, exec, s[84:85]
	s_cbranch_vccnz .Lwa_done
	s_andn2_b64 vcc, exec, s[66:67]
	s_cbranch_vccnz .Lwa_done
	s_add_i32 s99, s71, 1
	s_cmp_lg_u32 s71, 2
	s_cselect_b32 s99, s99, 0
	s_bitcmp1_b32 s2, 0
	s_cselect_b32 s0, 0x6400, 0
	v_add_u32_e32 v2, s0, v235
	v_add_u32_e32 v4, v2, v238
	v_add_u32_e32 v5, v2, v239
	v_add3_u32 v6, s0, v240, v236
	s_mul_i32 s4, s99, 0x4800
	v_add_u32_e32 v2, s4, v241
	v_add_u32_e32 v7, v2, v242
	v_add_u32_e32 v2, v2, v243
	s_add_i32 s5, s2, 1
	s_cmp_lt_u32 s5, s33
	s_cbranch_scc1 .Lwa_wait5
	s_waitcnt vmcnt(0)
	s_branch .Lwa_go

.Lwa_done:
	s_add_i32 s0, s92, 63
	s_cmp_le_u32 s0, s3
	s_cbranch_scc1 .LBB0_896
	v_mov_b32_e32 v2, v251
	s_nop 0
	v_cmp_gt_i32_e64 s[60:61], 22, v2
	v_cmp_gt_i32_e64 s[62:63], 23, v2
	v_cmp_gt_i32_e64 s[58:59], 21, v2
	s_and_b64 s[60:61], s[62:63], s[60:61]
	v_cmp_gt_i32_e64 s[56:57], 20, v2
	s_and_b64 s[58:59], s[60:61], s[58:59]
	v_cmp_gt_i32_e64 s[54:55], 19, v2
	s_and_b64 s[56:57], s[58:59], s[56:57]
	v_cmp_gt_i32_e64 s[52:53], 18, v2
	s_and_b64 s[54:55], s[56:57], s[54:55]
	v_cmp_gt_i32_e64 s[50:51], 17, v2
	s_and_b64 s[52:53], s[54:55], s[52:53]
	v_cmp_gt_i32_e64 s[48:49], 16, v2
	s_and_b64 s[50:51], s[52:53], s[50:51]
	v_cmp_gt_i32_e64 s[46:47], 7, v2
	s_and_b64 s[48:49], s[50:51], s[48:49]
	v_cmp_gt_i32_e64 s[44:45], 6, v2
	s_and_b64 s[46:47], s[48:49], s[46:47]
	v_cmp_gt_i32_e64 s[42:43], 5, v2
	s_and_b64 s[44:45], s[46:47], s[44:45]
	v_cmp_gt_i32_e64 s[40:41], 4, v2
	s_and_b64 s[42:43], s[44:45], s[42:43]
	v_cmp_gt_i32_e64 s[38:39], 3, v2
	s_and_b64 s[40:41], s[42:43], s[40:41]
	v_cmp_gt_i32_e64 s[36:37], 2, v2
	s_and_b64 s[38:39], s[40:41], s[38:39]
	v_cmp_gt_i32_e64 s[34:35], 1, v2
	s_and_b64 s[36:37], s[38:39], s[36:37]
	v_cmp_gt_i32_e64 s[30:31], 0, v2
	s_and_b64 s[34:35], s[36:37], s[34:35]
	s_and_b64 s[30:31], s[34:35], s[30:31]
	v_cmp_gt_i32_e64 s[26:27], 54, v2
	v_cndmask_b32_e64 v98, v98, v248, s[30:31]
	v_cmp_gt_i32_e64 s[30:31], 55, v2
	v_cmp_gt_i32_e64 s[24:25], 53, v2
	s_and_b64 s[26:27], s[30:31], s[26:27]
	v_cmp_gt_i32_e64 s[22:23], 52, v2
	s_and_b64 s[24:25], s[26:27], s[24:25]
	v_cmp_gt_i32_e64 s[20:21], 51, v2
	s_and_b64 s[22:23], s[24:25], s[22:23]
	v_cmp_gt_i32_e64 s[18:19], 50, v2
	s_and_b64 s[20:21], s[22:23], s[20:21]
	v_cmp_gt_i32_e64 s[16:17], 49, v2
	s_and_b64 s[18:19], s[20:21], s[18:19]
	v_cmp_gt_i32_e64 s[14:15], 48, v2
	s_and_b64 s[16:17], s[18:19], s[16:17]
	v_cmp_gt_i32_e64 s[12:13], 39, v2
	s_and_b64 s[14:15], s[16:17], s[14:15]
	v_cmp_gt_i32_e64 s[10:11], 38, v2
	s_and_b64 s[12:13], s[14:15], s[12:13]
	v_cmp_gt_i32_e64 s[8:9], 37, v2
	s_and_b64 s[10:11], s[12:13], s[10:11]
	v_cmp_gt_i32_e64 s[6:7], 36, v2
	s_and_b64 s[8:9], s[10:11], s[8:9]
	v_cmp_gt_i32_e64 s[4:5], 35, v2
	s_and_b64 s[6:7], s[8:9], s[6:7]
	v_cmp_gt_i32_e64 s[28:29], 34, v2
	s_and_b64 s[4:5], s[6:7], s[4:5]
	v_cmp_gt_i32_e64 s[0:1], 33, v2
	v_cndmask_b32_e64 v85, v85, v248, s[4:5]
	s_and_b64 s[4:5], s[4:5], s[28:29]
	v_cmp_gt_i32_e32 vcc, 32, v2
	s_and_b64 s[0:1], s[4:5], s[0:1]
	s_and_b64 vcc, s[0:1], vcc
	v_cndmask_b32_e64 v113, v113, v248, s[62:63]
	v_cndmask_b32_e64 v112, v112, v248, s[60:61]
	v_cndmask_b32_e64 v111, v111, v248, s[58:59]
	v_cndmask_b32_e64 v110, v110, v248, s[56:57]
	v_cndmask_b32_e64 v109, v109, v248, s[54:55]
	v_cndmask_b32_e64 v108, v108, v248, s[52:53]
	v_cndmask_b32_e64 v107, v107, v248, s[50:51]
	v_cndmask_b32_e64 v106, v106, v248, s[48:49]
	v_cndmask_b32_e64 v105, v105, v248, s[46:47]
	v_cndmask_b32_e64 v104, v104, v248, s[44:45]
	v_cndmask_b32_e64 v103, v103, v248, s[42:43]
	v_cndmask_b32_e64 v102, v102, v248, s[40:41]
	v_cndmask_b32_e64 v101, v101, v248, s[38:39]
	v_cndmask_b32_e64 v100, v100, v248, s[36:37]
	v_cndmask_b32_e64 v99, v99, v248, s[34:35]
	v_cndmask_b32_e64 v97, v97, v248, s[30:31]
	v_cndmask_b32_e64 v96, v96, v248, s[26:27]
	v_cndmask_b32_e64 v95, v95, v248, s[24:25]
	v_cndmask_b32_e64 v94, v94, v248, s[22:23]
	v_cndmask_b32_e64 v93, v93, v248, s[20:21]
	v_cndmask_b32_e64 v92, v92, v248, s[18:19]
	v_cndmask_b32_e64 v91, v91, v248, s[16:17]
	v_cndmask_b32_e64 v90, v90, v248, s[14:15]
	v_cndmask_b32_e64 v89, v89, v248, s[12:13]
	v_cndmask_b32_e64 v88, v88, v248, s[10:11]
	v_cndmask_b32_e64 v87, v87, v248, s[8:9]
	v_cndmask_b32_e64 v86, v86, v248, s[6:7]
	v_cndmask_b32_e64 v84, v84, v248, s[4:5]
	v_cndmask_b32_e64 v83, v83, v248, s[0:1]
	v_cndmask_b32_e32 v82, v82, v248, vcc

; __global__ void __launch_bounds__(512, 2) fwd_kernel(Args args) {
	.amdhsa_kernel _Z10fwd_kernel4Args
		.amdhsa_group_segment_fixed_size 0
		.amdhsa_private_segment_fixed_size 0
		.amdhsa_kernarg_size 528
		.amdhsa_user_sgpr_count 2
		.amdhsa_user_sgpr_dispatch_ptr 0
		.amdhsa_user_sgpr_queue_ptr 0
		.amdhsa_user_sgpr_kernarg_segment_ptr 1
		.amdhsa_user_sgpr_dispatch_id 0
		.amdhsa_user_sgpr_kernarg_preload_length 0
		.amdhsa_user_sgpr_kernarg_preload_offset 0
		.amdhsa_user_sgpr_private_segment_size 0
		.amdhsa_uses_dynamic_stack 0
		.amdhsa_enable_private_segment 0
		.amdhsa_system_sgpr_workgroup_id_x 1
		.amdhsa_system_sgpr_workgroup_id_y 0
		.amdhsa_system_sgpr_workgroup_id_z 0
		.amdhsa_system_sgpr_workgroup_info 0
		.amdhsa_system_vgpr_workitem_id 2
		.amdhsa_next_free_vgpr 256
		.amdhsa_next_free_sgpr 102
		.amdhsa_accum_offset 256
		.amdhsa_reserve_vcc 1
		.amdhsa_float_round_mode_32 0
		.amdhsa_float_round_mode_16_64 0
		.amdhsa_float_denorm_mode_32 3
		.amdhsa_float_denorm_mode_16_64 3
		.amdhsa_dx10_clamp 1
		.amdhsa_ieee_mode 1
		.amdhsa_fp16_overflow 0
		.amdhsa_tg_split 0
		.amdhsa_exception_fp_ieee_invalid_op 0
		.amdhsa_exception_fp_denorm_src 0
		.amdhsa_exception_fp_ieee_div_zero 0
		.amdhsa_exception_fp_ieee_overflow 0
		.amdhsa_exception_fp_ieee_underflow 0
		.amdhsa_exception_fp_ieee_inexact 0
		.amdhsa_exception_int_div_zero 0
	.end_amdhsa_kernel

; __global__ void __launch_bounds__(512, 2) fwd_kernel(Args args) {
amdhsa.kernels:
  - .agpr_count:     0
    .args:
      - .offset:         0
        .size:           272
        .value_kind:     by_value
      - .offset:         272
        .size:           4
        .value_kind:     hidden_block_count_x
      - .offset:         276
        .size:           4
        .value_kind:     hidden_block_count_y
      - .offset:         280
        .size:           4
        .value_kind:     hidden_block_count_z
      - .offset:         284
        .size:           2
        .value_kind:     hidden_group_size_x
      - .offset:         286
        .size:           2
        .value_kind:     hidden_group_size_y
      - .offset:         288
        .size:           2
        .value_kind:     hidden_group_size_z
      - .offset:         290
        .size:           2
        .value_kind:     hidden_remainder_x
      - .offset:         292
        .size:           2
        .value_kind:     hidden_remainder_y
      - .offset:         294
        .size:           2
        .value_kind:     hidden_remainder_z
      - .offset:         312
        .size:           8
        .value_kind:     hidden_global_offset_x
      - .offset:         320
        .size:           8
        .value_kind:     hidden_global_offset_y
      - .offset:         328
        .size:           8
        .value_kind:     hidden_global_offset_z
      - .offset:         336
        .size:           2
        .value_kind:     hidden_grid_dims
      - .offset:         360
        .size:           8
        .value_kind:     hidden_multigrid_sync_arg
      - .offset:         392
        .size:           4
        .value_kind:     hidden_dynamic_lds_size
    .group_segment_fixed_size: 0
    .kernarg_segment_align: 8
    .kernarg_segment_size: 528
    .language:       OpenCL C
    .language_version:
      - 2
      - 0
    .max_flat_workgroup_size: 512
    .name:           _Z10fwd_kernel4Args
    .private_segment_fixed_size: 0
    .sgpr_count:     108
    .sgpr_spill_count: 100
    .symbol:         _Z10fwd_kernel4Args.kd
    .uniform_work_group_size: 1
    .uses_dynamic_stack: false
    .vgpr_count:     256
    .vgpr_spill_count: 0
    .wavefront_size: 64
